# P3 prep item loop: guarded per-token load groups (tokens 4..15) all issued before a single wait; same conversions in same order
# speedup vs baseline: 1.0487x; 1.0101x over previous
.LBB0_950:
	s_or_b64 exec, exec, s[2:3]
	v_and_b32_e32 v63, 15, v120
	v_lshlrev_b32_e32 v61, 6, v63
	v_or_b32_e32 v50, v61, v121
	v_lshlrev_b64 v[18:19], 10, v[64:65]
	v_or_b32_e32 v2, v18, v50
	v_mov_b32_e32 v3, v19
	s_mov_b64 s[2:3], 0x400
	v_readlane_b32 s44, v245, 44
	v_lshlrev_b64 v[4:5], 1, v[2:3]
	v_lshl_add_u64 v[14:15], v[2:3], 0, s[2:3]
	v_lshlrev_b32_e32 v1, 2, v50
	v_readlane_b32 s52, v245, 52
	v_readlane_b32 s53, v245, 53
	v_lshl_add_u64 v[8:9], s[64:65], 0, v[4:5]
	v_lshlrev_b64 v[22:23], 1, v[14:15]
	v_readlane_b32 s54, v245, 54
	v_readlane_b32 s55, v245, 55
	v_readlane_b32 s56, v245, 56
	v_readlane_b32 s57, v245, 57
	global_load_dword v21, v1, s[52:53]
	s_nop 1
	global_load_dword v20, v1, s[54:55]
	s_nop 0
	global_load_dword v17, v1, s[56:57]
	v_lshl_add_u64 v[6:7], s[62:63], 0, v[4:5]
	v_lshl_add_u64 v[10:11], s[66:67], 0, v[4:5]
	v_lshl_add_u64 v[4:5], s[68:69], 0, v[4:5]
	v_lshl_add_u64 v[12:13], v[2:3], 2, s[70:71]
	v_lshl_add_u64 v[24:25], s[62:63], 0, v[22:23]
	v_lshl_add_u64 v[26:27], s[64:65], 0, v[22:23]
	v_lshl_add_u64 v[32:33], s[66:67], 0, v[22:23]
	global_load_ushort v101, v[8:9], off
	global_load_ushort v30, v[10:11], off
	global_load_ushort v102, v[4:5], off
	global_load_dword v29, v[12:13], off
	global_load_ushort v1, v[24:25], off
	global_load_ushort v99, v[26:27], off
	global_load_ushort v46, v[32:33], off
	global_load_ushort v16, v[6:7], off
	v_lshl_add_u64 v[8:9], v[2:3], 0, s[76:77]
	s_mov_b64 s[2:3], 0xc00
	v_lshlrev_b64 v[10:11], 1, v[8:9]
	v_lshl_add_u64 v[2:3], v[2:3], 0, s[2:3]
	v_lshl_add_u64 v[4:5], s[68:69], 0, v[22:23]
	v_lshl_add_u64 v[6:7], v[14:15], 2, s[70:71]
	v_lshl_add_u64 v[12:13], s[62:63], 0, v[10:11]
	v_lshl_add_u64 v[14:15], s[64:65], 0, v[10:11]
	v_lshl_add_u64 v[22:23], s[66:67], 0, v[10:11]
	v_lshl_add_u64 v[10:11], s[68:69], 0, v[10:11]
	v_lshlrev_b64 v[24:25], 1, v[2:3]
	v_lshl_add_u64 v[8:9], v[8:9], 2, s[70:71]
	v_lshl_add_u64 v[26:27], s[62:63], 0, v[24:25]
	global_load_ushort v100, v[4:5], off
	global_load_dword v97, v[6:7], off
	global_load_ushort v98, v[14:15], off
	global_load_ushort v94, v[22:23], off
	global_load_ushort v47, v[10:11], off
	global_load_dword v93, v[8:9], off
	s_nop 0
	global_load_ushort v10, v[26:27], off
	global_load_ushort v11, v[12:13], off
	v_lshl_add_u64 v[4:5], s[64:65], 0, v[24:25]
	v_lshl_add_u64 v[6:7], s[66:67], 0, v[24:25]
	v_lshl_add_u64 v[8:9], s[68:69], 0, v[24:25]
	v_lshl_add_u64 v[2:3], v[2:3], 2, s[70:71]
	global_load_ushort v96, v[4:5], off
	global_load_ushort v88, v[6:7], off
	global_load_ushort v95, v[8:9], off
	global_load_dword v90, v[2:3], off
	v_readlane_b32 s45, v245, 45
	v_readlane_b32 s46, v245, 46
	v_readlane_b32 s47, v245, 47
	v_readlane_b32 s48, v245, 48
	v_readlane_b32 s49, v245, 49
	v_readlane_b32 s50, v245, 50
	v_readlane_b32 s51, v245, 51
	v_readlane_b32 s58, v245, 58
	v_readlane_b32 s59, v245, 59
	s_waitcnt vmcnt(15)
	v_lshlrev_b32_e32 v1, 16, v1
	s_waitcnt vmcnt(12)
	v_lshlrev_b32_e32 v16, 16, v16
	s_waitcnt vmcnt(5)
	v_lshlrev_b32_e32 v3, 16, v10
	s_waitcnt vmcnt(4)
	v_lshlrev_b32_e32 v2, 16, v11
	s_and_saveexec_b64 s[2:3], s[82:83]
	s_xor_b64 s[2:3], exec, s[2:3]
	v_mov_b32_e32 v4, s86
	s_or_saveexec_b64 s[2:3], s[2:3]
	v_mov_b32_e32 v84, 0
	v_mov_b32_e32 v86, 0
	v_lshl_add_u64 v[18:19], v[18:19], 0, v[50:51]
	v_mov_b32_e32 v87, 0
	v_mov_b32_e32 v92, 0
	s_xor_b64 exec, exec, s[2:3]
	s_cbranch_execz .LBB0_954
	s_mov_b64 s[44:45], 0x1000
	v_lshl_add_u64 v[22:23], v[18:19], 0, s[44:45]
	v_lshlrev_b64 v[24:25], 1, v[22:23]
	v_lshl_add_u64 v[26:27], s[62:63], 0, v[24:25]
	v_lshl_add_u64 v[32:33], s[64:65], 0, v[24:25]
	v_lshl_add_u64 v[34:35], s[66:67], 0, v[24:25]
	v_lshl_add_u64 v[24:25], s[68:69], 0, v[24:25]
	v_lshl_add_u64 v[22:23], v[22:23], 2, s[70:71]
	global_load_ushort v176, v[26:27], off
	s_nop 0
	global_load_ushort v177, v[34:35], off
	s_nop 0
	global_load_ushort v178, v[24:25], off
	s_nop 0
	global_load_dword v179, v[22:23], off
	s_nop 0
	global_load_ushort v180, v[32:33], off
.LBB0_954:
	s_or_b64 exec, exec, s[2:3]
	s_and_saveexec_b64 s[2:3], s[82:83]
	s_xor_b64 s[2:3], exec, s[2:3]
	v_mov_b32_e32 v5, s86
	s_or_saveexec_b64 s[2:3], s[2:3]
	v_mov_b32_e32 v80, 0
	v_mov_b32_e32 v82, 0
	v_mov_b32_e32 v83, 0
	v_mov_b32_e32 v91, 0
	s_xor_b64 exec, exec, s[2:3]
	s_cbranch_execz .LBB0_958
	s_mov_b64 s[48:49], 0x1400
	v_lshl_add_u64 v[22:23], v[18:19], 0, s[48:49]
	v_lshlrev_b64 v[24:25], 1, v[22:23]
	v_lshl_add_u64 v[26:27], s[62:63], 0, v[24:25]
	v_lshl_add_u64 v[32:33], s[64:65], 0, v[24:25]
	v_lshl_add_u64 v[34:35], s[66:67], 0, v[24:25]
	v_lshl_add_u64 v[24:25], s[68:69], 0, v[24:25]
	v_lshl_add_u64 v[22:23], v[22:23], 2, s[70:71]
	global_load_ushort v181, v[26:27], off
	s_nop 0
	global_load_ushort v182, v[34:35], off
	s_nop 0
	global_load_ushort v183, v[24:25], off
	s_nop 0
	global_load_dword v184, v[22:23], off
	s_nop 0
	global_load_ushort v185, v[32:33], off
.LBB0_958:
	s_or_b64 exec, exec, s[2:3]
	s_and_saveexec_b64 s[2:3], s[82:83]
	s_xor_b64 s[2:3], exec, s[2:3]
	v_mov_b32_e32 v6, s86
	s_or_saveexec_b64 s[2:3], s[2:3]
	v_mov_b32_e32 v76, 0
	v_mov_b32_e32 v78, 0
	v_mov_b32_e32 v79, 0
	v_mov_b32_e32 v89, 0
	s_xor_b64 exec, exec, s[2:3]
	s_cbranch_execz .LBB0_962
	s_mov_b64 s[44:45], 0x1800
	v_lshl_add_u64 v[22:23], v[18:19], 0, s[44:45]
	v_lshlrev_b64 v[24:25], 1, v[22:23]
	v_lshl_add_u64 v[26:27], s[62:63], 0, v[24:25]
	v_lshl_add_u64 v[32:33], s[64:65], 0, v[24:25]
	v_lshl_add_u64 v[34:35], s[66:67], 0, v[24:25]
	v_lshl_add_u64 v[24:25], s[68:69], 0, v[24:25]
	v_lshl_add_u64 v[22:23], v[22:23], 2, s[70:71]
	global_load_ushort v186, v[26:27], off
	s_nop 0
	global_load_ushort v187, v[34:35], off
	s_nop 0
	global_load_ushort v188, v[24:25], off
	s_nop 0
	global_load_dword v189, v[22:23], off
	s_nop 0
	global_load_ushort v190, v[32:33], off
.LBB0_962:
	s_or_b64 exec, exec, s[2:3]
	s_and_saveexec_b64 s[2:3], s[82:83]
	s_xor_b64 s[2:3], exec, s[2:3]
	v_mov_b32_e32 v7, s86
	s_or_saveexec_b64 s[2:3], s[2:3]
	v_mov_b32_e32 v72, 0
	v_mov_b32_e32 v74, 0
	v_mov_b32_e32 v75, 0
	v_mov_b32_e32 v85, 0
	s_xor_b64 exec, exec, s[2:3]
	s_cbranch_execz .LBB0_966
	s_mov_b64 s[48:49], 0x1c00
	v_lshl_add_u64 v[22:23], v[18:19], 0, s[48:49]
	v_lshlrev_b64 v[24:25], 1, v[22:23]
	v_lshl_add_u64 v[26:27], s[62:63], 0, v[24:25]
	v_lshl_add_u64 v[32:33], s[64:65], 0, v[24:25]
	v_lshl_add_u64 v[34:35], s[66:67], 0, v[24:25]
	v_lshl_add_u64 v[24:25], s[68:69], 0, v[24:25]
	v_lshl_add_u64 v[22:23], v[22:23], 2, s[70:71]
	global_load_ushort v191, v[26:27], off
	s_nop 0
	global_load_ushort v192, v[34:35], off
	s_nop 0
	global_load_ushort v193, v[24:25], off
	s_nop 0
	global_load_dword v194, v[22:23], off
	s_nop 0
	global_load_ushort v195, v[32:33], off
.LBB0_966:
	s_or_b64 exec, exec, s[2:3]
	s_and_saveexec_b64 s[2:3], s[82:83]
	s_xor_b64 s[2:3], exec, s[2:3]
	v_mov_b32_e32 v8, s86
	s_or_saveexec_b64 s[2:3], s[2:3]
	v_mov_b32_e32 v68, 0
	v_mov_b32_e32 v69, 0
	v_mov_b32_e32 v70, 0
	v_mov_b32_e32 v81, 0
	s_xor_b64 exec, exec, s[2:3]
	s_cbranch_execz .LBB0_970
	s_mov_b64 s[44:45], 0x2000
	v_lshl_add_u64 v[22:23], v[18:19], 0, s[44:45]
	v_lshlrev_b64 v[24:25], 1, v[22:23]
	v_lshl_add_u64 v[26:27], s[62:63], 0, v[24:25]
	v_lshl_add_u64 v[32:33], s[64:65], 0, v[24:25]
	v_lshl_add_u64 v[34:35], s[66:67], 0, v[24:25]
	v_lshl_add_u64 v[24:25], s[68:69], 0, v[24:25]
	v_lshl_add_u64 v[22:23], v[22:23], 2, s[70:71]
	global_load_ushort v196, v[26:27], off
	s_nop 0
	global_load_ushort v197, v[34:35], off
	s_nop 0
	global_load_ushort v198, v[24:25], off
	s_nop 0
	global_load_dword v199, v[22:23], off
	s_nop 0
	global_load_ushort v200, v[32:33], off
.LBB0_970:
	s_or_b64 exec, exec, s[2:3]
	s_and_saveexec_b64 s[2:3], s[82:83]
	s_xor_b64 s[2:3], exec, s[2:3]
	v_mov_b32_e32 v9, s86
	s_or_saveexec_b64 s[2:3], s[2:3]
	v_mov_b32_e32 v45, 0
	v_mov_b32_e32 v48, 0
	v_mov_b32_e32 v49, 0
	v_mov_b32_e32 v77, 0
	s_xor_b64 exec, exec, s[2:3]
	s_cbranch_execz .LBB0_974
	s_mov_b64 s[48:49], 0x2400
	v_lshl_add_u64 v[22:23], v[18:19], 0, s[48:49]
	v_lshlrev_b64 v[24:25], 1, v[22:23]
	v_lshl_add_u64 v[26:27], s[62:63], 0, v[24:25]
	v_lshl_add_u64 v[32:33], s[64:65], 0, v[24:25]
	v_lshl_add_u64 v[34:35], s[66:67], 0, v[24:25]
	v_lshl_add_u64 v[24:25], s[68:69], 0, v[24:25]
	v_lshl_add_u64 v[22:23], v[22:23], 2, s[70:71]
	global_load_ushort v201, v[26:27], off
	s_nop 0
	global_load_ushort v202, v[34:35], off
	s_nop 0
	global_load_ushort v203, v[24:25], off
	s_nop 0
	global_load_dword v204, v[22:23], off
	s_nop 0
	global_load_ushort v205, v[32:33], off
	s_waitcnt vmcnt(30)
.LBB0_974:
	s_or_b64 exec, exec, s[2:3]
	s_and_saveexec_b64 s[2:3], s[82:83]
	s_xor_b64 s[2:3], exec, s[2:3]
	v_mov_b32_e32 v10, s86
	s_or_saveexec_b64 s[2:3], s[2:3]
	v_mov_b32_e32 v40, 0
	v_mov_b32_e32 v42, 0
	v_mov_b32_e32 v43, 0
	v_mov_b32_e32 v73, 0
	s_xor_b64 exec, exec, s[2:3]
	s_cbranch_execz .LBB0_978
	s_mov_b64 s[48:49], 0x2800
	v_lshl_add_u64 v[22:23], v[18:19], 0, s[48:49]
	v_lshlrev_b64 v[24:25], 1, v[22:23]
	v_lshl_add_u64 v[26:27], s[62:63], 0, v[24:25]
	v_lshl_add_u64 v[32:33], s[64:65], 0, v[24:25]
	v_lshl_add_u64 v[34:35], s[66:67], 0, v[24:25]
	v_lshl_add_u64 v[24:25], s[68:69], 0, v[24:25]
	v_lshl_add_u64 v[22:23], v[22:23], 2, s[70:71]
	global_load_ushort v206, v[26:27], off
	s_nop 0
	global_load_ushort v207, v[34:35], off
	s_nop 0
	global_load_ushort v208, v[24:25], off
	s_nop 0
	global_load_dword v209, v[22:23], off
	s_nop 0
	global_load_ushort v210, v[32:33], off
.LBB0_978:
	s_or_b64 exec, exec, s[2:3]
	s_and_saveexec_b64 s[2:3], s[82:83]
	s_xor_b64 s[2:3], exec, s[2:3]
	v_mov_b32_e32 v11, s86
	s_or_saveexec_b64 s[2:3], s[2:3]
	v_mov_b32_e32 v37, 0
	v_mov_b32_e32 v39, 0
	v_mov_b32_e32 v41, 0
	v_mov_b32_e32 v71, 0
	s_xor_b64 exec, exec, s[2:3]
	s_cbranch_execz .LBB0_982
	s_mov_b64 s[48:49], 0x2c00
	v_lshl_add_u64 v[22:23], v[18:19], 0, s[48:49]
	v_lshlrev_b64 v[24:25], 1, v[22:23]
	v_lshl_add_u64 v[26:27], s[62:63], 0, v[24:25]
	v_lshl_add_u64 v[32:33], s[66:67], 0, v[24:25]
	global_load_ushort v211, v[26:27], off
	global_load_ushort v212, v[32:33], off
	v_lshl_add_u64 v[26:27], s[64:65], 0, v[24:25]
	v_lshl_add_u64 v[24:25], s[68:69], 0, v[24:25]
	global_load_ushort v213, v[24:25], off
	s_nop 0
	global_load_ushort v214, v[26:27], off
	v_lshl_add_u64 v[22:23], v[22:23], 2, s[70:71]
	global_load_dword v215, v[22:23], off
.LBB0_982:
	s_or_b64 exec, exec, s[2:3]
	s_and_saveexec_b64 s[2:3], s[82:83]
	s_xor_b64 s[2:3], exec, s[2:3]
	v_mov_b32_e32 v12, s86
	s_or_saveexec_b64 s[2:3], s[2:3]
	v_mov_b32_e32 v33, 0
	v_mov_b32_e32 v35, 0
	v_mov_b32_e32 v36, 0
	v_mov_b32_e32 v67, 0
	s_xor_b64 exec, exec, s[2:3]
	s_cbranch_execz .LBB0_986
	s_mov_b64 s[48:49], 0x3000
	v_lshl_add_u64 v[22:23], v[18:19], 0, s[48:49]
	v_lshlrev_b64 v[24:25], 1, v[22:23]
	v_lshl_add_u64 v[26:27], s[62:63], 0, v[24:25]
	v_lshl_add_u64 v[32:33], s[64:65], 0, v[24:25]
	v_lshl_add_u64 v[34:35], s[66:67], 0, v[24:25]
	v_lshl_add_u64 v[24:25], s[68:69], 0, v[24:25]
	v_lshl_add_u64 v[22:23], v[22:23], 2, s[70:71]
	global_load_ushort v216, v[26:27], off
	s_nop 0
	global_load_ushort v217, v[34:35], off
	s_nop 0
	global_load_ushort v218, v[24:25], off
	s_nop 0
	global_load_dword v219, v[22:23], off
	s_nop 0
	global_load_ushort v220, v[32:33], off
.LBB0_986:
	s_or_b64 exec, exec, s[2:3]
	s_and_saveexec_b64 s[2:3], s[82:83]
	s_xor_b64 s[2:3], exec, s[2:3]
	v_mov_b32_e32 v13, s86
	s_or_saveexec_b64 s[2:3], s[2:3]
	v_mov_b32_e32 v28, 0
	v_mov_b32_e32 v31, 0
	v_mov_b32_e32 v32, 0
	v_mov_b32_e32 v44, 0
	s_xor_b64 exec, exec, s[2:3]
	s_cbranch_execz .LBB0_990
	s_mov_b64 s[48:49], 0x3400
	v_lshl_add_u64 v[22:23], v[18:19], 0, s[48:49]
	v_lshlrev_b64 v[24:25], 1, v[22:23]
	v_lshl_add_u64 v[26:27], s[62:63], 0, v[24:25]
	v_lshl_add_u64 v[104:105], s[64:65], 0, v[24:25]
	v_lshl_add_u64 v[106:107], s[66:67], 0, v[24:25]
	v_lshl_add_u64 v[24:25], s[68:69], 0, v[24:25]
	v_lshl_add_u64 v[22:23], v[22:23], 2, s[70:71]
	global_load_ushort v221, v[26:27], off
	s_nop 0
	global_load_ushort v222, v[106:107], off
	s_nop 0
	global_load_ushort v223, v[24:25], off
	s_nop 0
	global_load_dword v224, v[22:23], off
	s_nop 0
	global_load_ushort v225, v[104:105], off
.LBB0_990:
	s_or_b64 exec, exec, s[2:3]
	s_and_saveexec_b64 s[2:3], s[82:83]
	s_xor_b64 s[2:3], exec, s[2:3]
	v_mov_b32_e32 v14, s86
	s_or_saveexec_b64 s[2:3], s[2:3]
	v_mov_b32_e32 v25, 0
	v_mov_b32_e32 v26, 0
	v_mov_b32_e32 v27, 0
	v_mov_b32_e32 v38, 0
	s_xor_b64 exec, exec, s[2:3]
	s_cbranch_execz .LBB0_994
	s_mov_b64 s[48:49], 0x3800
	v_lshl_add_u64 v[22:23], v[18:19], 0, s[48:49]
	v_lshlrev_b64 v[24:25], 1, v[22:23]
	v_lshl_add_u64 v[26:27], s[62:63], 0, v[24:25]
	v_lshl_add_u64 v[104:105], s[64:65], 0, v[24:25]
	v_lshl_add_u64 v[106:107], s[66:67], 0, v[24:25]
	v_lshl_add_u64 v[24:25], s[68:69], 0, v[24:25]
	v_lshl_add_u64 v[22:23], v[22:23], 2, s[70:71]
	global_load_ushort v226, v[26:27], off
	s_nop 0
	global_load_ushort v227, v[106:107], off
	s_nop 0
	global_load_ushort v228, v[24:25], off
	s_nop 0
	global_load_dword v229, v[22:23], off
	s_nop 0
	global_load_ushort v230, v[104:105], off
.LBB0_994:
	s_or_b64 exec, exec, s[2:3]
	s_and_saveexec_b64 s[2:3], s[82:83]
	s_xor_b64 s[2:3], exec, s[2:3]
	v_mov_b32_e32 v15, s86
	s_or_saveexec_b64 s[2:3], s[2:3]
	v_mov_b32_e32 v22, 0
	v_mov_b32_e32 v23, 0
	v_mov_b32_e32 v24, 0
	v_mov_b32_e32 v34, 0
	s_xor_b64 exec, exec, s[2:3]
	s_cbranch_execz .LBB0_998
	s_mov_b64 s[48:49], 0x3c00
	v_lshl_add_u64 v[18:19], v[18:19], 0, s[48:49]
	v_lshlrev_b64 v[22:23], 1, v[18:19]
	v_lshl_add_u64 v[104:105], s[62:63], 0, v[22:23]
	v_lshl_add_u64 v[106:107], s[64:65], 0, v[22:23]
	v_lshl_add_u64 v[108:109], s[66:67], 0, v[22:23]
	v_lshl_add_u64 v[22:23], s[68:69], 0, v[22:23]
	v_lshl_add_u64 v[18:19], v[18:19], 2, s[70:71]
	global_load_ushort v231, v[104:105], off
	global_load_ushort v232, v[108:109], off
	s_nop 0
	global_load_ushort v233, v[22:23], off
	s_nop 0
	global_load_dword v234, v[18:19], off
	s_nop 0
	global_load_ushort v235, v[106:107], off
.LBB0_998:
	s_or_b64 exec, exec, s[2:3]
	s_waitcnt vmcnt(0)
	s_mov_b64 s[2:3], exec
	s_andn2_b64 exec, exec, s[82:83]
	v_lshlrev_b32_e32 v4, 16, v176
	v_lshlrev_b32_e32 v23, 16, v177
	v_lshlrev_b32_e32 v87, 16, v178
	v_cvt_pk_bf16_f32 v84, v23, s0
	v_lshlrev_b32_e32 v92, 16, v180
	v_mov_b32_e32 v26, v177
	v_mov_b32_e32 v24, v178
	v_mov_b32_e32 v86, v179
	v_mov_b32_e32 v22, v180
	v_lshlrev_b32_e32 v5, 16, v181
	v_lshlrev_b32_e32 v23, 16, v182
	v_lshlrev_b32_e32 v83, 16, v183
	v_cvt_pk_bf16_f32 v80, v23, s0
	v_lshlrev_b32_e32 v91, 16, v185
	v_mov_b32_e32 v26, v182
	v_mov_b32_e32 v24, v183
	v_mov_b32_e32 v82, v184
	v_mov_b32_e32 v22, v185
	v_lshlrev_b32_e32 v6, 16, v186
	v_lshlrev_b32_e32 v23, 16, v187
	v_lshlrev_b32_e32 v79, 16, v188
	v_cvt_pk_bf16_f32 v76, v23, s0
	v_lshlrev_b32_e32 v89, 16, v190
	v_mov_b32_e32 v26, v187
	v_mov_b32_e32 v24, v188
	v_mov_b32_e32 v78, v189
	v_mov_b32_e32 v22, v190
	v_lshlrev_b32_e32 v7, 16, v191
	v_lshlrev_b32_e32 v23, 16, v192
	v_lshlrev_b32_e32 v75, 16, v193
	v_cvt_pk_bf16_f32 v72, v23, s0
	v_lshlrev_b32_e32 v85, 16, v195
	v_mov_b32_e32 v26, v192
	v_mov_b32_e32 v24, v193
	v_mov_b32_e32 v74, v194
	v_mov_b32_e32 v22, v195
	v_lshlrev_b32_e32 v8, 16, v196
	v_lshlrev_b32_e32 v23, 16, v197
	v_lshlrev_b32_e32 v70, 16, v198
	v_cvt_pk_bf16_f32 v68, v23, s0
	v_lshlrev_b32_e32 v81, 16, v200
	v_mov_b32_e32 v26, v197
	v_mov_b32_e32 v24, v198
	v_mov_b32_e32 v69, v199
	v_mov_b32_e32 v22, v200
	v_lshlrev_b32_e32 v9, 16, v201
	v_lshlrev_b32_e32 v23, 16, v202
	v_lshlrev_b32_e32 v49, 16, v203
	v_cvt_pk_bf16_f32 v45, v23, s0
	v_lshlrev_b32_e32 v77, 16, v205
	v_mov_b32_e32 v26, v202
	v_mov_b32_e32 v24, v203
	v_mov_b32_e32 v48, v204
	v_mov_b32_e32 v22, v205
	v_lshlrev_b32_e32 v10, 16, v206
	v_lshlrev_b32_e32 v23, 16, v207
	v_lshlrev_b32_e32 v43, 16, v208
	v_cvt_pk_bf16_f32 v40, v23, s0
	v_lshlrev_b32_e32 v73, 16, v210
	v_mov_b32_e32 v26, v207
	v_mov_b32_e32 v24, v208
	v_mov_b32_e32 v42, v209
	v_mov_b32_e32 v22, v210
	v_lshlrev_b32_e32 v11, 16, v211
	v_lshlrev_b32_e32 v22, 16, v212
	v_cvt_pk_bf16_f32 v37, v22, s0
	v_lshlrev_b32_e32 v41, 16, v213
	v_lshlrev_b32_e32 v71, 16, v214
	v_mov_b32_e32 v28, v212
	v_mov_b32_e32 v24, v213
	v_mov_b32_e32 v25, v214
	v_mov_b32_e32 v39, v215
	v_lshlrev_b32_e32 v12, 16, v216
	v_lshlrev_b32_e32 v23, 16, v217
	v_lshlrev_b32_e32 v36, 16, v218
	v_cvt_pk_bf16_f32 v33, v23, s0
	v_lshlrev_b32_e32 v67, 16, v220
	v_mov_b32_e32 v26, v217
	v_mov_b32_e32 v24, v218
	v_mov_b32_e32 v35, v219
	v_mov_b32_e32 v22, v220
	v_lshlrev_b32_e32 v13, 16, v221
	v_lshlrev_b32_e32 v23, 16, v222
	v_lshlrev_b32_e32 v32, 16, v223
	v_cvt_pk_bf16_f32 v28, v23, s0
	v_lshlrev_b32_e32 v44, 16, v225
	v_mov_b32_e32 v26, v222
	v_mov_b32_e32 v24, v223
	v_mov_b32_e32 v31, v224
	v_mov_b32_e32 v22, v225
	v_lshlrev_b32_e32 v14, 16, v226
	v_lshlrev_b32_e32 v23, 16, v227
	v_lshlrev_b32_e32 v27, 16, v228
	v_cvt_pk_bf16_f32 v25, v23, s0
	v_lshlrev_b32_e32 v38, 16, v230
	v_mov_b32_e32 v24, v228
	v_mov_b32_e32 v26, v229
	v_mov_b32_e32 v22, v230
	v_lshlrev_b32_e32 v15, 16, v231
	v_lshlrev_b32_e32 v19, 16, v232
	v_lshlrev_b32_e32 v24, 16, v233
	v_cvt_pk_bf16_f32 v22, v19, s0
	v_lshlrev_b32_e32 v34, 16, v235
	v_mov_b32_e32 v23, v234
	v_mov_b32_e32 v18, v235
	s_mov_b64 exec, s[2:3]
	v_lshlrev_b32_e32 v103, 16, v101
	v_lshlrev_b32_e32 v50, 2, v63
	v_lshl_add_u64 v[18:19], s[72:73], 0, v[50:51]
	v_mul_f32_e32 v50, v21, v103
	v_lshlrev_b32_e32 v101, 16, v102
	v_mul_f32_e32 v102, v50, v50
	s_nop 1
	v_mov_b32_dpp v102, v102 quad_perm:[1,0,3,2] row_mask:0xf bank_mask:0xf bound_ctrl:1
	v_fmac_f32_e32 v102, v50, v50
	s_nop 1
	v_add_f32_dpp v102, v102, v102 quad_perm:[2,3,0,1] row_mask:0xf bank_mask:0xf bound_ctrl:1
	s_nop 1
	v_add_f32_dpp v102, v102, v102 row_half_mirror row_mask:0xf bank_mask:0xf bound_ctrl:1
	s_nop 1
	v_add_f32_dpp v102, v102, v102 row_mirror row_mask:0xf bank_mask:0xf bound_ctrl:1
	s_nop 0
	v_readlane_b32 s33, v102, 0
	v_readlane_b32 s85, v102, 16
	v_readlane_b32 s84, v102, 32
	v_readlane_b32 s89, v102, 48
	v_add_f32_e32 v102, -1.0, v101
	v_fma_f32 v102, v20, v102, 1.0
	v_mul_f32_e32 v102, v102, v103
	v_mul_f32_e32 v103, v102, v16
	v_mul_f32_e32 v104, v17, v103
	s_nop 1
	v_mov_b32_dpp v104, v104 quad_perm:[1,0,3,2] row_mask:0xf bank_mask:0xf bound_ctrl:1
	v_fmac_f32_e32 v104, v17, v103
	s_nop 1
	v_add_f32_dpp v103, v104, v104 quad_perm:[2,3,0,1] row_mask:0xf bank_mask:0xf bound_ctrl:1
	v_lshlrev_b64 v[104:105], 6, v[64:65]
	v_lshl_add_u64 v[18:19], v[18:19], 0, v[104:105]
	v_add_f32_dpp v103, v103, v103 row_half_mirror row_mask:0xf bank_mask:0xf bound_ctrl:1
	s_nop 1
	v_add_f32_dpp v103, v103, v103 row_mirror row_mask:0xf bank_mask:0xf bound_ctrl:1
	s_nop 0
	v_readlane_b32 s2, v103, 0
	v_readlane_b32 s90, v103, 16
	v_readlane_b32 s3, v103, 32
	v_readlane_b32 s91, v103, 48
	s_and_saveexec_b64 s[48:49], s[0:1]
	s_cbranch_execz .LBB0_1000
	v_mov_b32_e32 v104, s90
	v_mov_b32_e32 v105, s91
	v_pk_add_f32 v[104:105], s[2:3], v[104:105]
	s_nop 0
	v_add_f32_e32 v103, v104, v105
	global_store_dword v[18:19], v103, off
